# lever 1: attention K/V streaming loop no longer drains all LDS-DMA loads at the loop top (the template's counted waits remain)
# speedup vs baseline: 1.0070x; 1.0070x over previous
.LBB0_246:
	s_and_b32 s6, s31, 0x6000
	s_add_i32 s7, s6, s35
	s_add_i32 s6, s6, s34
	s_nop 0
	v_lshl_add_u64 v[12:13], v[2:3], 0, s[2:3]
	s_mov_b32 s38, m0
	s_mov_b32 m0, s6
	s_nop 0
	global_load_lds_dwordx4 v[12:13], off
	s_mov_b32 m0, s38
	v_lshl_add_u64 v[10:11], v[4:5], 0, s[2:3]
	s_mov_b32 s6, m0
	s_mov_b32 m0, s7
	s_nop 0
	global_load_lds_dwordx4 v[10:11], off
	s_mov_b32 m0, s6
	s_cmp_ge_u32 s30, s53
	s_mov_b64 s[6:7], -1
	s_cbranch_scc0 .LBB0_248
	s_waitcnt vmcnt(2) lgkmcnt(0)
	s_barrier
	s_mov_b64 s[6:7], 0
